# S5 item: C-table copy done by waves 1-7 while wave 0 runs the f64 stage (all loads in flight at once), copy loop behind that stage removed
# speedup vs baseline: 1.0031x; 1.0031x over previous
.Lssa_466:
	s_or_b64 exec, exec, s[84:85]
	v_readfirstlane_b32 s98, v208
	s_cmp_lt_u32 s98, 64
	s_cbranch_scc1 .Lcct_skip
	v_subrev_u32_e32 v48, 64, v208
	s_lshl_b32 s98, s82, 12
	v_lshl_add_u32 v49, v48, 2, s98
	global_load_dword v52, v49, s[16:17]
	global_load_dword v53, v49, s[18:19]
	global_load_dword v54, v49, s[16:17] offset:1792
	global_load_dword v55, v49, s[18:19] offset:1792
	v_cmp_gt_u32_e32 vcc, 128, v48
	s_and_saveexec_b64 s[84:85], vcc
	global_load_dword v58, v49, s[16:17] offset:3584
	global_load_dword v59, v49, s[18:19] offset:3584
	s_or_b64 exec, exec, s[84:85]
	v_lshrrev_b32_e32 v51, 6, v48
	v_and_b32_e32 v51, 7, v51
	v_lshlrev_b32_e32 v51, 4, v51
	v_lshlrev_b32_e32 v50, 3, v48
	v_xor_b32_e32 v50, v51, v50
	v_add_u32_e32 v56, 0x1c0, v48
	v_lshrrev_b32_e32 v51, 6, v56
	v_and_b32_e32 v51, 7, v51
	v_lshlrev_b32_e32 v51, 4, v51
	v_lshlrev_b32_e32 v57, 3, v56
	v_xor_b32_e32 v57, v51, v57
	v_add_u32_e32 v60, 0x380, v48
	v_lshrrev_b32_e32 v51, 6, v60
	v_and_b32_e32 v51, 7, v51
	v_lshlrev_b32_e32 v51, 4, v51
	v_lshlrev_b32_e32 v61, 3, v60
	v_xor_b32_e32 v61, v51, v61
	s_waitcnt vmcnt(0)
	ds_write_b64 v50, v[52:53] offset:16896
	ds_write_b64 v57, v[54:55] offset:16896
	s_and_saveexec_b64 s[84:85], vcc
	ds_write_b64 v61, v[58:59] offset:16896
	s_or_b64 exec, exec, s[84:85]
.Lcct_skip:
	s_waitcnt lgkmcnt(0)
	s_barrier
	ds_read_b128 v[50:53], v78 offset:25088
	s_mov_b64 s[84:85], 0
	v_mov_b32_e32 v8, v71
	v_mov_b32_e32 v37, v208
	s_waitcnt lgkmcnt(0)
	v_mul_f64 v[48:49], v[52:53], v[52:53]
	v_mov_b64_e32 v[4:5], v[50:51]
	v_fma_f64 v[6:7], 0, v[50:51], v[52:53]
	v_fma_f64 v[48:49], v[50:51], v[50:51], -v[48:49]
	v_add_f64 v[50:51], v[50:51], v[50:51]
	v_mul_f64 v[50:51], v[52:53], v[50:51]
	v_fmac_f64_e32 v[4:5], 0x80000000, v[52:53]
	v_mul_f64 v[52:53], v[50:51], v[50:51]
	v_add_f64 v[54:55], v[48:49], v[48:49]
	v_fma_f64 v[52:53], v[48:49], v[48:49], -v[52:53]
	v_mul_f64 v[54:55], v[50:51], v[54:55]
	v_mul_f64 v[56:57], v[54:55], v[54:55]
	v_add_f64 v[58:59], v[52:53], v[52:53]
	v_fma_f64 v[56:57], v[52:53], v[52:53], -v[56:57]
	v_mul_f64 v[58:59], v[54:55], v[58:59]
	v_mul_f64 v[60:61], v[58:59], v[58:59]
	v_add_f64 v[62:63], v[56:57], v[56:57]
	v_fma_f64 v[60:61], v[56:57], v[56:57], -v[60:61]
	v_mul_f64 v[62:63], v[58:59], v[62:63]

.Lssa_469:
	global_load_dword v56, v[6:7], off
	global_load_dword v54, v[48:49], off
	v_and_b32_e32 v50, 0xfc, v8
	v_lshl_or_b32 v51, v8, 3, 24
	v_lshl_add_u32 v50, v50, 3, 0
	v_add_u32_e32 v52, 0, v51
	ds_read_b64 v[50:51], v50 offset:25104
	ds_read_b64 v[52:53], v52 offset:25088
	v_add_co_u32_e32 v44, vcc, 0x200, v44
	s_xor_b64 s[84:85], vcc, -1
	s_and_b64 s[84:85], exec, s[84:85]
	v_lshl_add_u64 v[6:7], v[6:7], 0, s[80:81]
	v_lshl_add_u64 v[48:49], v[48:49], 0, s[80:81]
	v_add_u32_e32 v8, 0x80, v8
	s_or_b64 s[4:5], s[84:85], s[4:5]
	s_waitcnt vmcnt(1)
	v_cvt_f64_f32_e32 v[56:57], v56
	s_waitcnt vmcnt(0)
	v_cvt_f64_f32_e32 v[54:55], v54
	s_waitcnt lgkmcnt(0)
	v_mul_f64 v[58:59], v[52:53], v[56:57]
	v_mul_f64 v[56:57], v[50:51], v[56:57]
	v_fma_f64 v[50:51], v[50:51], v[54:55], -v[58:59]
	v_fmac_f64_e32 v[56:57], v[52:53], v[54:55]
	v_cvt_f32_f64_e32 v50, v[50:51]
	v_cvt_f32_f64_e32 v51, v[56:57]
	ds_write_b64 v37, v[50:51]
	v_add_u32_e32 v37, 0x1000, v37
	s_andn2_b64 exec, exec, s[4:5]
	s_cbranch_execnz .Lssa_469
	s_or_b64 exec, exec, s[4:5]
	v_readfirstlane_b32 s98, v208
	s_lshr_b32 s98, s98, 6
	v_and_b32_e32 v12, 15, v210
	v_lshrrev_b32_e32 v13, 4, v210
	s_load_dwordx2 s[84:85], s[22:23], 0x80
	v_lshl_add_u32 v18, s82, 4, v12
	v_lshlrev_b32_e32 v18, 2, v18
	s_waitcnt lgkmcnt(0)
	global_load_dword v18, v18, s[84:85]
	v_lshrrev_b32_e32 v19, 1, v13
	v_lshl_add_u32 v14, v19, 4, v12
	v_lshlrev_b32_e32 v14, 3, v14
	v_and_b32_e32 v15, 1, v13
	v_lshl_add_u32 v14, v15, 2, v14
	v_cmp_eq_u32_e64 s[84:85], 1, v15
	s_lshl_b32 s4, s98, 10
	v_lshl_add_u32 v16, v19, 3, s4
	v_and_b32_e32 v15, 7, v12
	v_lshlrev_b32_e32 v15, 4, v15
	v_lshl_add_u32 v15, v12, 9, v15
	v_lshl_add_u32 v15, v19, 3, v15
	s_lshl_b32 s4, s98, 11
	v_lshl_add_u32 v17, v13, 8, s4
	v_lshl_add_u32 v17, v12, 2, v17
	v_mov_b32_e32 v20, 0
	v_mov_b32_e32 v21, 0
	v_mov_b32_e32 v22, 0
	v_mov_b32_e32 v23, 0
	v_mov_b32_e32 v24, 0
	v_mov_b32_e32 v25, 0
	v_mov_b32_e32 v26, 0
	v_mov_b32_e32 v27, 0
	s_waitcnt lgkmcnt(0)
	s_barrier
	ds_read_b64 v[30:31], v15 offset:16896
	ds_read_b64 v[32:33], v16 offset:0
	ds_read_b64 v[34:35], v16 offset:512
	ds_read_b32 v28, v14 offset:8704
	v_xor_b32_e32 v19, 0x10, v15
	ds_read_b64 v[52:53], v19 offset:16896
	ds_read_b64 v[54:55], v16 offset:16
	ds_read_b64 v[56:57], v16 offset:528
	ds_read_b32 v29, v14 offset:8960
	s_waitcnt lgkmcnt(4)
	v_pk_mul_f32 v[58:59], v[30:31], v[32:33] op_sel:[1,1] op_sel_hi:[0,1]
	v_pk_fma_f32 v[58:59], v[30:31], v[32:33], v[58:59] op_sel_hi:[1,0,1] neg_lo:[0,0,1]
	v_pk_mul_f32 v[60:61], v[30:31], v[34:35] op_sel:[1,1] op_sel_hi:[0,1]
	v_pk_fma_f32 v[60:61], v[30:31], v[34:35], v[60:61] op_sel_hi:[1,0,1] neg_lo:[0,0,1]
	v_cndmask_b32_e64 v62, v58, -v59, s[84:85]
	v_cndmask_b32_e64 v63, v60, -v61, s[84:85]
	s_nop 1
	v_mfma_f32_16x16x4_f32 v[20:23], v62, v28, v[20:23]
	v_mfma_f32_16x16x4_f32 v[24:27], v63, v28, v[24:27]
	v_xor_b32_e32 v19, 0x20, v15
	ds_read_b64 v[30:31], v19 offset:16896
	ds_read_b64 v[32:33], v16 offset:32
	ds_read_b64 v[34:35], v16 offset:544
	ds_read_b32 v28, v14 offset:9216
	s_waitcnt lgkmcnt(4)
	v_pk_mul_f32 v[58:59], v[52:53], v[54:55] op_sel:[1,1] op_sel_hi:[0,1]
	v_pk_fma_f32 v[58:59], v[52:53], v[54:55], v[58:59] op_sel_hi:[1,0,1] neg_lo:[0,0,1]
	v_pk_mul_f32 v[60:61], v[52:53], v[56:57] op_sel:[1,1] op_sel_hi:[0,1]
	v_pk_fma_f32 v[60:61], v[52:53], v[56:57], v[60:61] op_sel_hi:[1,0,1] neg_lo:[0,0,1]
	v_cndmask_b32_e64 v62, v58, -v59, s[84:85]
	v_cndmask_b32_e64 v63, v60, -v61, s[84:85]
	s_nop 1
	v_mfma_f32_16x16x4_f32 v[20:23], v62, v29, v[20:23]
	v_mfma_f32_16x16x4_f32 v[24:27], v63, v29, v[24:27]
	v_xor_b32_e32 v19, 0x30, v15
	ds_read_b64 v[52:53], v19 offset:16896
	ds_read_b64 v[54:55], v16 offset:48
	ds_read_b64 v[56:57], v16 offset:560
	ds_read_b32 v29, v14 offset:9472
	s_waitcnt lgkmcnt(4)
	v_pk_mul_f32 v[58:59], v[30:31], v[32:33] op_sel:[1,1] op_sel_hi:[0,1]
	v_pk_fma_f32 v[58:59], v[30:31], v[32:33], v[58:59] op_sel_hi:[1,0,1] neg_lo:[0,0,1]
	v_pk_mul_f32 v[60:61], v[30:31], v[34:35] op_sel:[1,1] op_sel_hi:[0,1]
	v_pk_fma_f32 v[60:61], v[30:31], v[34:35], v[60:61] op_sel_hi:[1,0,1] neg_lo:[0,0,1]
	v_cndmask_b32_e64 v62, v58, -v59, s[84:85]
	v_cndmask_b32_e64 v63, v60, -v61, s[84:85]
	s_nop 1
	v_mfma_f32_16x16x4_f32 v[20:23], v62, v28, v[20:23]
	v_mfma_f32_16x16x4_f32 v[24:27], v63, v28, v[24:27]
	v_xor_b32_e32 v19, 0x40, v15
	ds_read_b64 v[30:31], v19 offset:16896
	ds_read_b64 v[32:33], v16 offset:64
	ds_read_b64 v[34:35], v16 offset:576
	ds_read_b32 v28, v14 offset:9728
	s_waitcnt lgkmcnt(4)
	v_pk_mul_f32 v[58:59], v[52:53], v[54:55] op_sel:[1,1] op_sel_hi:[0,1]
	v_pk_fma_f32 v[58:59], v[52:53], v[54:55], v[58:59] op_sel_hi:[1,0,1] neg_lo:[0,0,1]
	v_pk_mul_f32 v[60:61], v[52:53], v[56:57] op_sel:[1,1] op_sel_hi:[0,1]
	v_pk_fma_f32 v[60:61], v[52:53], v[56:57], v[60:61] op_sel_hi:[1,0,1] neg_lo:[0,0,1]
	v_cndmask_b32_e64 v62, v58, -v59, s[84:85]
	v_cndmask_b32_e64 v63, v60, -v61, s[84:85]
	s_nop 1
	v_mfma_f32_16x16x4_f32 v[20:23], v62, v29, v[20:23]
	v_mfma_f32_16x16x4_f32 v[24:27], v63, v29, v[24:27]
	v_xor_b32_e32 v19, 0x50, v15
	ds_read_b64 v[52:53], v19 offset:16896
	ds_read_b64 v[54:55], v16 offset:80
	ds_read_b64 v[56:57], v16 offset:592
	ds_read_b32 v29, v14 offset:9984
	s_waitcnt lgkmcnt(4)
	v_pk_mul_f32 v[58:59], v[30:31], v[32:33] op_sel:[1,1] op_sel_hi:[0,1]
	v_pk_fma_f32 v[58:59], v[30:31], v[32:33], v[58:59] op_sel_hi:[1,0,1] neg_lo:[0,0,1]
	v_pk_mul_f32 v[60:61], v[30:31], v[34:35] op_sel:[1,1] op_sel_hi:[0,1]
	v_pk_fma_f32 v[60:61], v[30:31], v[34:35], v[60:61] op_sel_hi:[1,0,1] neg_lo:[0,0,1]
	v_cndmask_b32_e64 v62, v58, -v59, s[84:85]
	v_cndmask_b32_e64 v63, v60, -v61, s[84:85]
	s_nop 1
	v_mfma_f32_16x16x4_f32 v[20:23], v62, v28, v[20:23]
	v_mfma_f32_16x16x4_f32 v[24:27], v63, v28, v[24:27]
	v_xor_b32_e32 v19, 0x60, v15
	ds_read_b64 v[30:31], v19 offset:16896
	ds_read_b64 v[32:33], v16 offset:96
	ds_read_b64 v[34:35], v16 offset:608
	ds_read_b32 v28, v14 offset:10240
	s_waitcnt lgkmcnt(4)
	v_pk_mul_f32 v[58:59], v[52:53], v[54:55] op_sel:[1,1] op_sel_hi:[0,1]
	v_pk_fma_f32 v[58:59], v[52:53], v[54:55], v[58:59] op_sel_hi:[1,0,1] neg_lo:[0,0,1]
	v_pk_mul_f32 v[60:61], v[52:53], v[56:57] op_sel:[1,1] op_sel_hi:[0,1]
	v_pk_fma_f32 v[60:61], v[52:53], v[56:57], v[60:61] op_sel_hi:[1,0,1] neg_lo:[0,0,1]
	v_cndmask_b32_e64 v62, v58, -v59, s[84:85]
	v_cndmask_b32_e64 v63, v60, -v61, s[84:85]
	s_nop 1
	v_mfma_f32_16x16x4_f32 v[20:23], v62, v29, v[20:23]
	v_mfma_f32_16x16x4_f32 v[24:27], v63, v29, v[24:27]
	v_xor_b32_e32 v19, 0x70, v15
	ds_read_b64 v[52:53], v19 offset:16896
	ds_read_b64 v[54:55], v16 offset:112
	ds_read_b64 v[56:57], v16 offset:624
	ds_read_b32 v29, v14 offset:10496
	s_waitcnt lgkmcnt(4)
	v_pk_mul_f32 v[58:59], v[30:31], v[32:33] op_sel:[1,1] op_sel_hi:[0,1]
	v_pk_fma_f32 v[58:59], v[30:31], v[32:33], v[58:59] op_sel_hi:[1,0,1] neg_lo:[0,0,1]
	v_pk_mul_f32 v[60:61], v[30:31], v[34:35] op_sel:[1,1] op_sel_hi:[0,1]
	v_pk_fma_f32 v[60:61], v[30:31], v[34:35], v[60:61] op_sel_hi:[1,0,1] neg_lo:[0,0,1]
	v_cndmask_b32_e64 v62, v58, -v59, s[84:85]
	v_cndmask_b32_e64 v63, v60, -v61, s[84:85]
	s_nop 1
	v_mfma_f32_16x16x4_f32 v[20:23], v62, v28, v[20:23]
	v_mfma_f32_16x16x4_f32 v[24:27], v63, v28, v[24:27]
	v_xor_b32_e32 v19, 0x80, v15
	ds_read_b64 v[30:31], v19 offset:16896
	ds_read_b64 v[32:33], v16 offset:128
	ds_read_b64 v[34:35], v16 offset:640
	ds_read_b32 v28, v14 offset:10752
	s_waitcnt lgkmcnt(4)
	v_pk_mul_f32 v[58:59], v[52:53], v[54:55] op_sel:[1,1] op_sel_hi:[0,1]
	v_pk_fma_f32 v[58:59], v[52:53], v[54:55], v[58:59] op_sel_hi:[1,0,1] neg_lo:[0,0,1]
	v_pk_mul_f32 v[60:61], v[52:53], v[56:57] op_sel:[1,1] op_sel_hi:[0,1]
	v_pk_fma_f32 v[60:61], v[52:53], v[56:57], v[60:61] op_sel_hi:[1,0,1] neg_lo:[0,0,1]
	v_cndmask_b32_e64 v62, v58, -v59, s[84:85]
	v_cndmask_b32_e64 v63, v60, -v61, s[84:85]
	s_nop 1
	v_mfma_f32_16x16x4_f32 v[20:23], v62, v29, v[20:23]
	v_mfma_f32_16x16x4_f32 v[24:27], v63, v29, v[24:27]
	v_xor_b32_e32 v19, 0x90, v15
	ds_read_b64 v[52:53], v19 offset:16896
	ds_read_b64 v[54:55], v16 offset:144
	ds_read_b64 v[56:57], v16 offset:656
	ds_read_b32 v29, v14 offset:11008
	s_waitcnt lgkmcnt(4)
	v_pk_mul_f32 v[58:59], v[30:31], v[32:33] op_sel:[1,1] op_sel_hi:[0,1]
	v_pk_fma_f32 v[58:59], v[30:31], v[32:33], v[58:59] op_sel_hi:[1,0,1] neg_lo:[0,0,1]
	v_pk_mul_f32 v[60:61], v[30:31], v[34:35] op_sel:[1,1] op_sel_hi:[0,1]
	v_pk_fma_f32 v[60:61], v[30:31], v[34:35], v[60:61] op_sel_hi:[1,0,1] neg_lo:[0,0,1]
	v_cndmask_b32_e64 v62, v58, -v59, s[84:85]
	v_cndmask_b32_e64 v63, v60, -v61, s[84:85]
	s_nop 1
	v_mfma_f32_16x16x4_f32 v[20:23], v62, v28, v[20:23]
	v_mfma_f32_16x16x4_f32 v[24:27], v63, v28, v[24:27]
	v_xor_b32_e32 v19, 0xa0, v15
	ds_read_b64 v[30:31], v19 offset:16896
	ds_read_b64 v[32:33], v16 offset:160
	ds_read_b64 v[34:35], v16 offset:672
	ds_read_b32 v28, v14 offset:11264
	s_waitcnt lgkmcnt(4)
	v_pk_mul_f32 v[58:59], v[52:53], v[54:55] op_sel:[1,1] op_sel_hi:[0,1]
	v_pk_fma_f32 v[58:59], v[52:53], v[54:55], v[58:59] op_sel_hi:[1,0,1] neg_lo:[0,0,1]
	v_pk_mul_f32 v[60:61], v[52:53], v[56:57] op_sel:[1,1] op_sel_hi:[0,1]
	v_pk_fma_f32 v[60:61], v[52:53], v[56:57], v[60:61] op_sel_hi:[1,0,1] neg_lo:[0,0,1]
	v_cndmask_b32_e64 v62, v58, -v59, s[84:85]
	v_cndmask_b32_e64 v63, v60, -v61, s[84:85]
	s_nop 1
	v_mfma_f32_16x16x4_f32 v[20:23], v62, v29, v[20:23]
	v_mfma_f32_16x16x4_f32 v[24:27], v63, v29, v[24:27]
	v_xor_b32_e32 v19, 0xb0, v15
	ds_read_b64 v[52:53], v19 offset:16896
	ds_read_b64 v[54:55], v16 offset:176
	ds_read_b64 v[56:57], v16 offset:688
	ds_read_b32 v29, v14 offset:11520
	s_waitcnt lgkmcnt(4)
	v_pk_mul_f32 v[58:59], v[30:31], v[32:33] op_sel:[1,1] op_sel_hi:[0,1]
	v_pk_fma_f32 v[58:59], v[30:31], v[32:33], v[58:59] op_sel_hi:[1,0,1] neg_lo:[0,0,1]
	v_pk_mul_f32 v[60:61], v[30:31], v[34:35] op_sel:[1,1] op_sel_hi:[0,1]
	v_pk_fma_f32 v[60:61], v[30:31], v[34:35], v[60:61] op_sel_hi:[1,0,1] neg_lo:[0,0,1]
	v_cndmask_b32_e64 v62, v58, -v59, s[84:85]
	v_cndmask_b32_e64 v63, v60, -v61, s[84:85]
	s_nop 1
	v_mfma_f32_16x16x4_f32 v[20:23], v62, v28, v[20:23]
	v_mfma_f32_16x16x4_f32 v[24:27], v63, v28, v[24:27]
	v_xor_b32_e32 v19, 0xc0, v15
	ds_read_b64 v[30:31], v19 offset:16896
	ds_read_b64 v[32:33], v16 offset:192
	ds_read_b64 v[34:35], v16 offset:704
	ds_read_b32 v28, v14 offset:11776
	s_waitcnt lgkmcnt(4)
	v_pk_mul_f32 v[58:59], v[52:53], v[54:55] op_sel:[1,1] op_sel_hi:[0,1]
	v_pk_fma_f32 v[58:59], v[52:53], v[54:55], v[58:59] op_sel_hi:[1,0,1] neg_lo:[0,0,1]
	v_pk_mul_f32 v[60:61], v[52:53], v[56:57] op_sel:[1,1] op_sel_hi:[0,1]
	v_pk_fma_f32 v[60:61], v[52:53], v[56:57], v[60:61] op_sel_hi:[1,0,1] neg_lo:[0,0,1]
	v_cndmask_b32_e64 v62, v58, -v59, s[84:85]
	v_cndmask_b32_e64 v63, v60, -v61, s[84:85]
	s_nop 1
	v_mfma_f32_16x16x4_f32 v[20:23], v62, v29, v[20:23]
	v_mfma_f32_16x16x4_f32 v[24:27], v63, v29, v[24:27]
	v_xor_b32_e32 v19, 0xd0, v15
	ds_read_b64 v[52:53], v19 offset:16896
	ds_read_b64 v[54:55], v16 offset:208
	ds_read_b64 v[56:57], v16 offset:720
	ds_read_b32 v29, v14 offset:12032
	s_waitcnt lgkmcnt(4)
	v_pk_mul_f32 v[58:59], v[30:31], v[32:33] op_sel:[1,1] op_sel_hi:[0,1]
	v_pk_fma_f32 v[58:59], v[30:31], v[32:33], v[58:59] op_sel_hi:[1,0,1] neg_lo:[0,0,1]
	v_pk_mul_f32 v[60:61], v[30:31], v[34:35] op_sel:[1,1] op_sel_hi:[0,1]
	v_pk_fma_f32 v[60:61], v[30:31], v[34:35], v[60:61] op_sel_hi:[1,0,1] neg_lo:[0,0,1]
	v_cndmask_b32_e64 v62, v58, -v59, s[84:85]
	v_cndmask_b32_e64 v63, v60, -v61, s[84:85]
	s_nop 1
	v_mfma_f32_16x16x4_f32 v[20:23], v62, v28, v[20:23]
	v_mfma_f32_16x16x4_f32 v[24:27], v63, v28, v[24:27]
	v_xor_b32_e32 v19, 0xe0, v15
	ds_read_b64 v[30:31], v19 offset:16896
	ds_read_b64 v[32:33], v16 offset:224
	ds_read_b64 v[34:35], v16 offset:736
	ds_read_b32 v28, v14 offset:12288
	s_waitcnt lgkmcnt(4)
	v_pk_mul_f32 v[58:59], v[52:53], v[54:55] op_sel:[1,1] op_sel_hi:[0,1]
	v_pk_fma_f32 v[58:59], v[52:53], v[54:55], v[58:59] op_sel_hi:[1,0,1] neg_lo:[0,0,1]
	v_pk_mul_f32 v[60:61], v[52:53], v[56:57] op_sel:[1,1] op_sel_hi:[0,1]
	v_pk_fma_f32 v[60:61], v[52:53], v[56:57], v[60:61] op_sel_hi:[1,0,1] neg_lo:[0,0,1]
	v_cndmask_b32_e64 v62, v58, -v59, s[84:85]
	v_cndmask_b32_e64 v63, v60, -v61, s[84:85]
	s_nop 1
	v_mfma_f32_16x16x4_f32 v[20:23], v62, v29, v[20:23]
	v_mfma_f32_16x16x4_f32 v[24:27], v63, v29, v[24:27]
	v_xor_b32_e32 v19, 0xf0, v15
	ds_read_b64 v[52:53], v19 offset:16896
	ds_read_b64 v[54:55], v16 offset:240
	ds_read_b64 v[56:57], v16 offset:752
	ds_read_b32 v29, v14 offset:12544
	s_waitcnt lgkmcnt(4)
	v_pk_mul_f32 v[58:59], v[30:31], v[32:33] op_sel:[1,1] op_sel_hi:[0,1]
	v_pk_fma_f32 v[58:59], v[30:31], v[32:33], v[58:59] op_sel_hi:[1,0,1] neg_lo:[0,0,1]
	v_pk_mul_f32 v[60:61], v[30:31], v[34:35] op_sel:[1,1] op_sel_hi:[0,1]
	v_pk_fma_f32 v[60:61], v[30:31], v[34:35], v[60:61] op_sel_hi:[1,0,1] neg_lo:[0,0,1]
	v_cndmask_b32_e64 v62, v58, -v59, s[84:85]
	v_cndmask_b32_e64 v63, v60, -v61, s[84:85]
	s_nop 1
	v_mfma_f32_16x16x4_f32 v[20:23], v62, v28, v[20:23]
	v_mfma_f32_16x16x4_f32 v[24:27], v63, v28, v[24:27]
	v_xor_b32_e32 v19, 0x100, v15
	ds_read_b64 v[30:31], v19 offset:16896
	ds_read_b64 v[32:33], v16 offset:256
	ds_read_b64 v[34:35], v16 offset:768
	ds_read_b32 v28, v14 offset:12800
	s_waitcnt lgkmcnt(4)
	v_pk_mul_f32 v[58:59], v[52:53], v[54:55] op_sel:[1,1] op_sel_hi:[0,1]
	v_pk_fma_f32 v[58:59], v[52:53], v[54:55], v[58:59] op_sel_hi:[1,0,1] neg_lo:[0,0,1]
	v_pk_mul_f32 v[60:61], v[52:53], v[56:57] op_sel:[1,1] op_sel_hi:[0,1]
	v_pk_fma_f32 v[60:61], v[52:53], v[56:57], v[60:61] op_sel_hi:[1,0,1] neg_lo:[0,0,1]
	v_cndmask_b32_e64 v62, v58, -v59, s[84:85]
	v_cndmask_b32_e64 v63, v60, -v61, s[84:85]
	s_nop 1
	v_mfma_f32_16x16x4_f32 v[20:23], v62, v29, v[20:23]
	v_mfma_f32_16x16x4_f32 v[24:27], v63, v29, v[24:27]
	v_xor_b32_e32 v19, 0x110, v15
	ds_read_b64 v[52:53], v19 offset:16896
	ds_read_b64 v[54:55], v16 offset:272
	ds_read_b64 v[56:57], v16 offset:784
	ds_read_b32 v29, v14 offset:13056
	s_waitcnt lgkmcnt(4)
	v_pk_mul_f32 v[58:59], v[30:31], v[32:33] op_sel:[1,1] op_sel_hi:[0,1]
	v_pk_fma_f32 v[58:59], v[30:31], v[32:33], v[58:59] op_sel_hi:[1,0,1] neg_lo:[0,0,1]
	v_pk_mul_f32 v[60:61], v[30:31], v[34:35] op_sel:[1,1] op_sel_hi:[0,1]
	v_pk_fma_f32 v[60:61], v[30:31], v[34:35], v[60:61] op_sel_hi:[1,0,1] neg_lo:[0,0,1]
	v_cndmask_b32_e64 v62, v58, -v59, s[84:85]
	v_cndmask_b32_e64 v63, v60, -v61, s[84:85]
	s_nop 1
	v_mfma_f32_16x16x4_f32 v[20:23], v62, v28, v[20:23]
	v_mfma_f32_16x16x4_f32 v[24:27], v63, v28, v[24:27]
	v_xor_b32_e32 v19, 0x120, v15
	ds_read_b64 v[30:31], v19 offset:16896
	ds_read_b64 v[32:33], v16 offset:288
	ds_read_b64 v[34:35], v16 offset:800
	ds_read_b32 v28, v14 offset:13312
	s_waitcnt lgkmcnt(4)
	v_pk_mul_f32 v[58:59], v[52:53], v[54:55] op_sel:[1,1] op_sel_hi:[0,1]
	v_pk_fma_f32 v[58:59], v[52:53], v[54:55], v[58:59] op_sel_hi:[1,0,1] neg_lo:[0,0,1]
	v_pk_mul_f32 v[60:61], v[52:53], v[56:57] op_sel:[1,1] op_sel_hi:[0,1]
	v_pk_fma_f32 v[60:61], v[52:53], v[56:57], v[60:61] op_sel_hi:[1,0,1] neg_lo:[0,0,1]
	v_cndmask_b32_e64 v62, v58, -v59, s[84:85]
	v_cndmask_b32_e64 v63, v60, -v61, s[84:85]
	s_nop 1
	v_mfma_f32_16x16x4_f32 v[20:23], v62, v29, v[20:23]
	v_mfma_f32_16x16x4_f32 v[24:27], v63, v29, v[24:27]
	v_xor_b32_e32 v19, 0x130, v15
	ds_read_b64 v[52:53], v19 offset:16896
	ds_read_b64 v[54:55], v16 offset:304
	ds_read_b64 v[56:57], v16 offset:816
	ds_read_b32 v29, v14 offset:13568
	s_waitcnt lgkmcnt(4)
	v_pk_mul_f32 v[58:59], v[30:31], v[32:33] op_sel:[1,1] op_sel_hi:[0,1]
	v_pk_fma_f32 v[58:59], v[30:31], v[32:33], v[58:59] op_sel_hi:[1,0,1] neg_lo:[0,0,1]
	v_pk_mul_f32 v[60:61], v[30:31], v[34:35] op_sel:[1,1] op_sel_hi:[0,1]
	v_pk_fma_f32 v[60:61], v[30:31], v[34:35], v[60:61] op_sel_hi:[1,0,1] neg_lo:[0,0,1]
	v_cndmask_b32_e64 v62, v58, -v59, s[84:85]
	v_cndmask_b32_e64 v63, v60, -v61, s[84:85]
	s_nop 1
	v_mfma_f32_16x16x4_f32 v[20:23], v62, v28, v[20:23]
	v_mfma_f32_16x16x4_f32 v[24:27], v63, v28, v[24:27]
	v_xor_b32_e32 v19, 0x140, v15
	ds_read_b64 v[30:31], v19 offset:16896
	ds_read_b64 v[32:33], v16 offset:320
	ds_read_b64 v[34:35], v16 offset:832
	ds_read_b32 v28, v14 offset:13824
	s_waitcnt lgkmcnt(4)
	v_pk_mul_f32 v[58:59], v[52:53], v[54:55] op_sel:[1,1] op_sel_hi:[0,1]
	v_pk_fma_f32 v[58:59], v[52:53], v[54:55], v[58:59] op_sel_hi:[1,0,1] neg_lo:[0,0,1]
	v_pk_mul_f32 v[60:61], v[52:53], v[56:57] op_sel:[1,1] op_sel_hi:[0,1]
	v_pk_fma_f32 v[60:61], v[52:53], v[56:57], v[60:61] op_sel_hi:[1,0,1] neg_lo:[0,0,1]
	v_cndmask_b32_e64 v62, v58, -v59, s[84:85]
	v_cndmask_b32_e64 v63, v60, -v61, s[84:85]
	s_nop 1
	v_mfma_f32_16x16x4_f32 v[20:23], v62, v29, v[20:23]
	v_mfma_f32_16x16x4_f32 v[24:27], v63, v29, v[24:27]
	v_xor_b32_e32 v19, 0x150, v15
	ds_read_b64 v[52:53], v19 offset:16896
	ds_read_b64 v[54:55], v16 offset:336
	ds_read_b64 v[56:57], v16 offset:848
	ds_read_b32 v29, v14 offset:14080
	s_waitcnt lgkmcnt(4)
	v_pk_mul_f32 v[58:59], v[30:31], v[32:33] op_sel:[1,1] op_sel_hi:[0,1]
	v_pk_fma_f32 v[58:59], v[30:31], v[32:33], v[58:59] op_sel_hi:[1,0,1] neg_lo:[0,0,1]
	v_pk_mul_f32 v[60:61], v[30:31], v[34:35] op_sel:[1,1] op_sel_hi:[0,1]
	v_pk_fma_f32 v[60:61], v[30:31], v[34:35], v[60:61] op_sel_hi:[1,0,1] neg_lo:[0,0,1]
	v_cndmask_b32_e64 v62, v58, -v59, s[84:85]
	v_cndmask_b32_e64 v63, v60, -v61, s[84:85]
	s_nop 1
	v_mfma_f32_16x16x4_f32 v[20:23], v62, v28, v[20:23]
	v_mfma_f32_16x16x4_f32 v[24:27], v63, v28, v[24:27]
	v_xor_b32_e32 v19, 0x160, v15
	ds_read_b64 v[30:31], v19 offset:16896
	ds_read_b64 v[32:33], v16 offset:352
	ds_read_b64 v[34:35], v16 offset:864
	ds_read_b32 v28, v14 offset:14336
	s_waitcnt lgkmcnt(4)
	v_pk_mul_f32 v[58:59], v[52:53], v[54:55] op_sel:[1,1] op_sel_hi:[0,1]
	v_pk_fma_f32 v[58:59], v[52:53], v[54:55], v[58:59] op_sel_hi:[1,0,1] neg_lo:[0,0,1]
	v_pk_mul_f32 v[60:61], v[52:53], v[56:57] op_sel:[1,1] op_sel_hi:[0,1]
	v_pk_fma_f32 v[60:61], v[52:53], v[56:57], v[60:61] op_sel_hi:[1,0,1] neg_lo:[0,0,1]
	v_cndmask_b32_e64 v62, v58, -v59, s[84:85]
	v_cndmask_b32_e64 v63, v60, -v61, s[84:85]
	s_nop 1
	v_mfma_f32_16x16x4_f32 v[20:23], v62, v29, v[20:23]
	v_mfma_f32_16x16x4_f32 v[24:27], v63, v29, v[24:27]
	v_xor_b32_e32 v19, 0x170, v15
	ds_read_b64 v[52:53], v19 offset:16896
	ds_read_b64 v[54:55], v16 offset:368
	ds_read_b64 v[56:57], v16 offset:880
	ds_read_b32 v29, v14 offset:14592
	s_waitcnt lgkmcnt(4)
	v_pk_mul_f32 v[58:59], v[30:31], v[32:33] op_sel:[1,1] op_sel_hi:[0,1]
	v_pk_fma_f32 v[58:59], v[30:31], v[32:33], v[58:59] op_sel_hi:[1,0,1] neg_lo:[0,0,1]
	v_pk_mul_f32 v[60:61], v[30:31], v[34:35] op_sel:[1,1] op_sel_hi:[0,1]
	v_pk_fma_f32 v[60:61], v[30:31], v[34:35], v[60:61] op_sel_hi:[1,0,1] neg_lo:[0,0,1]
	v_cndmask_b32_e64 v62, v58, -v59, s[84:85]
	v_cndmask_b32_e64 v63, v60, -v61, s[84:85]
	s_nop 1
	v_mfma_f32_16x16x4_f32 v[20:23], v62, v28, v[20:23]
	v_mfma_f32_16x16x4_f32 v[24:27], v63, v28, v[24:27]
	v_xor_b32_e32 v19, 0x180, v15
	ds_read_b64 v[30:31], v19 offset:16896
	ds_read_b64 v[32:33], v16 offset:384
	ds_read_b64 v[34:35], v16 offset:896
	ds_read_b32 v28, v14 offset:14848
	s_waitcnt lgkmcnt(4)
	v_pk_mul_f32 v[58:59], v[52:53], v[54:55] op_sel:[1,1] op_sel_hi:[0,1]
	v_pk_fma_f32 v[58:59], v[52:53], v[54:55], v[58:59] op_sel_hi:[1,0,1] neg_lo:[0,0,1]
	v_pk_mul_f32 v[60:61], v[52:53], v[56:57] op_sel:[1,1] op_sel_hi:[0,1]
	v_pk_fma_f32 v[60:61], v[52:53], v[56:57], v[60:61] op_sel_hi:[1,0,1] neg_lo:[0,0,1]
	v_cndmask_b32_e64 v62, v58, -v59, s[84:85]
	v_cndmask_b32_e64 v63, v60, -v61, s[84:85]
	s_nop 1
	v_mfma_f32_16x16x4_f32 v[20:23], v62, v29, v[20:23]
	v_mfma_f32_16x16x4_f32 v[24:27], v63, v29, v[24:27]
	v_xor_b32_e32 v19, 0x190, v15
	ds_read_b64 v[52:53], v19 offset:16896
	ds_read_b64 v[54:55], v16 offset:400
	ds_read_b64 v[56:57], v16 offset:912
	ds_read_b32 v29, v14 offset:15104
	s_waitcnt lgkmcnt(4)
	v_pk_mul_f32 v[58:59], v[30:31], v[32:33] op_sel:[1,1] op_sel_hi:[0,1]
	v_pk_fma_f32 v[58:59], v[30:31], v[32:33], v[58:59] op_sel_hi:[1,0,1] neg_lo:[0,0,1]
	v_pk_mul_f32 v[60:61], v[30:31], v[34:35] op_sel:[1,1] op_sel_hi:[0,1]
	v_pk_fma_f32 v[60:61], v[30:31], v[34:35], v[60:61] op_sel_hi:[1,0,1] neg_lo:[0,0,1]
	v_cndmask_b32_e64 v62, v58, -v59, s[84:85]
	v_cndmask_b32_e64 v63, v60, -v61, s[84:85]
	s_nop 1
	v_mfma_f32_16x16x4_f32 v[20:23], v62, v28, v[20:23]
	v_mfma_f32_16x16x4_f32 v[24:27], v63, v28, v[24:27]
	v_xor_b32_e32 v19, 0x1a0, v15
	ds_read_b64 v[30:31], v19 offset:16896
	ds_read_b64 v[32:33], v16 offset:416
	ds_read_b64 v[34:35], v16 offset:928
	ds_read_b32 v28, v14 offset:15360
	s_waitcnt lgkmcnt(4)
	v_pk_mul_f32 v[58:59], v[52:53], v[54:55] op_sel:[1,1] op_sel_hi:[0,1]
	v_pk_fma_f32 v[58:59], v[52:53], v[54:55], v[58:59] op_sel_hi:[1,0,1] neg_lo:[0,0,1]
	v_pk_mul_f32 v[60:61], v[52:53], v[56:57] op_sel:[1,1] op_sel_hi:[0,1]
	v_pk_fma_f32 v[60:61], v[52:53], v[56:57], v[60:61] op_sel_hi:[1,0,1] neg_lo:[0,0,1]
	v_cndmask_b32_e64 v62, v58, -v59, s[84:85]
	v_cndmask_b32_e64 v63, v60, -v61, s[84:85]
	s_nop 1
	v_mfma_f32_16x16x4_f32 v[20:23], v62, v29, v[20:23]
	v_mfma_f32_16x16x4_f32 v[24:27], v63, v29, v[24:27]
	v_xor_b32_e32 v19, 0x1b0, v15
	ds_read_b64 v[52:53], v19 offset:16896
	ds_read_b64 v[54:55], v16 offset:432
	ds_read_b64 v[56:57], v16 offset:944
	ds_read_b32 v29, v14 offset:15616
	s_waitcnt lgkmcnt(4)
	v_pk_mul_f32 v[58:59], v[30:31], v[32:33] op_sel:[1,1] op_sel_hi:[0,1]
	v_pk_fma_f32 v[58:59], v[30:31], v[32:33], v[58:59] op_sel_hi:[1,0,1] neg_lo:[0,0,1]
	v_pk_mul_f32 v[60:61], v[30:31], v[34:35] op_sel:[1,1] op_sel_hi:[0,1]
	v_pk_fma_f32 v[60:61], v[30:31], v[34:35], v[60:61] op_sel_hi:[1,0,1] neg_lo:[0,0,1]
	v_cndmask_b32_e64 v62, v58, -v59, s[84:85]
	v_cndmask_b32_e64 v63, v60, -v61, s[84:85]
	s_nop 1
	v_mfma_f32_16x16x4_f32 v[20:23], v62, v28, v[20:23]
	v_mfma_f32_16x16x4_f32 v[24:27], v63, v28, v[24:27]
	v_xor_b32_e32 v19, 0x1c0, v15
	ds_read_b64 v[30:31], v19 offset:16896
	ds_read_b64 v[32:33], v16 offset:448
	ds_read_b64 v[34:35], v16 offset:960
	ds_read_b32 v28, v14 offset:15872
	s_waitcnt lgkmcnt(4)
	v_pk_mul_f32 v[58:59], v[52:53], v[54:55] op_sel:[1,1] op_sel_hi:[0,1]
	v_pk_fma_f32 v[58:59], v[52:53], v[54:55], v[58:59] op_sel_hi:[1,0,1] neg_lo:[0,0,1]
	v_pk_mul_f32 v[60:61], v[52:53], v[56:57] op_sel:[1,1] op_sel_hi:[0,1]
	v_pk_fma_f32 v[60:61], v[52:53], v[56:57], v[60:61] op_sel_hi:[1,0,1] neg_lo:[0,0,1]
	v_cndmask_b32_e64 v62, v58, -v59, s[84:85]
	v_cndmask_b32_e64 v63, v60, -v61, s[84:85]
	s_nop 1
	v_mfma_f32_16x16x4_f32 v[20:23], v62, v29, v[20:23]
	v_mfma_f32_16x16x4_f32 v[24:27], v63, v29, v[24:27]
	v_xor_b32_e32 v19, 0x1d0, v15
	ds_read_b64 v[52:53], v19 offset:16896
	ds_read_b64 v[54:55], v16 offset:464
	ds_read_b64 v[56:57], v16 offset:976
	ds_read_b32 v29, v14 offset:16128
	s_waitcnt lgkmcnt(4)
	v_pk_mul_f32 v[58:59], v[30:31], v[32:33] op_sel:[1,1] op_sel_hi:[0,1]
	v_pk_fma_f32 v[58:59], v[30:31], v[32:33], v[58:59] op_sel_hi:[1,0,1] neg_lo:[0,0,1]
	v_pk_mul_f32 v[60:61], v[30:31], v[34:35] op_sel:[1,1] op_sel_hi:[0,1]
	v_pk_fma_f32 v[60:61], v[30:31], v[34:35], v[60:61] op_sel_hi:[1,0,1] neg_lo:[0,0,1]
	v_cndmask_b32_e64 v62, v58, -v59, s[84:85]
	v_cndmask_b32_e64 v63, v60, -v61, s[84:85]
	s_nop 1
	v_mfma_f32_16x16x4_f32 v[20:23], v62, v28, v[20:23]
	v_mfma_f32_16x16x4_f32 v[24:27], v63, v28, v[24:27]
	v_xor_b32_e32 v19, 0x1e0, v15
	ds_read_b64 v[30:31], v19 offset:16896
	ds_read_b64 v[32:33], v16 offset:480
	ds_read_b64 v[34:35], v16 offset:992
	ds_read_b32 v28, v14 offset:16384
	s_waitcnt lgkmcnt(4)
	v_pk_mul_f32 v[58:59], v[52:53], v[54:55] op_sel:[1,1] op_sel_hi:[0,1]
	v_pk_fma_f32 v[58:59], v[52:53], v[54:55], v[58:59] op_sel_hi:[1,0,1] neg_lo:[0,0,1]
	v_pk_mul_f32 v[60:61], v[52:53], v[56:57] op_sel:[1,1] op_sel_hi:[0,1]
	v_pk_fma_f32 v[60:61], v[52:53], v[56:57], v[60:61] op_sel_hi:[1,0,1] neg_lo:[0,0,1]
	v_cndmask_b32_e64 v62, v58, -v59, s[84:85]
	v_cndmask_b32_e64 v63, v60, -v61, s[84:85]
	s_nop 1
	v_mfma_f32_16x16x4_f32 v[20:23], v62, v29, v[20:23]
	v_mfma_f32_16x16x4_f32 v[24:27], v63, v29, v[24:27]
	v_xor_b32_e32 v19, 0x1f0, v15
	ds_read_b64 v[52:53], v19 offset:16896
	ds_read_b64 v[54:55], v16 offset:496
	ds_read_b64 v[56:57], v16 offset:1008
	ds_read_b32 v29, v14 offset:16640
	s_waitcnt lgkmcnt(4)
	v_pk_mul_f32 v[58:59], v[30:31], v[32:33] op_sel:[1,1] op_sel_hi:[0,1]
	v_pk_fma_f32 v[58:59], v[30:31], v[32:33], v[58:59] op_sel_hi:[1,0,1] neg_lo:[0,0,1]
	v_pk_mul_f32 v[60:61], v[30:31], v[34:35] op_sel:[1,1] op_sel_hi:[0,1]
	v_pk_fma_f32 v[60:61], v[30:31], v[34:35], v[60:61] op_sel_hi:[1,0,1] neg_lo:[0,0,1]
	v_cndmask_b32_e64 v62, v58, -v59, s[84:85]
	v_cndmask_b32_e64 v63, v60, -v61, s[84:85]
	s_nop 1
	v_mfma_f32_16x16x4_f32 v[20:23], v62, v28, v[20:23]
	v_mfma_f32_16x16x4_f32 v[24:27], v63, v28, v[24:27]
	s_waitcnt lgkmcnt(0)
	v_pk_mul_f32 v[58:59], v[52:53], v[54:55] op_sel:[1,1] op_sel_hi:[0,1]
	v_pk_fma_f32 v[58:59], v[52:53], v[54:55], v[58:59] op_sel_hi:[1,0,1] neg_lo:[0,0,1]
	v_pk_mul_f32 v[60:61], v[52:53], v[56:57] op_sel:[1,1] op_sel_hi:[0,1]
	v_pk_fma_f32 v[60:61], v[52:53], v[56:57], v[60:61] op_sel_hi:[1,0,1] neg_lo:[0,0,1]
	v_cndmask_b32_e64 v62, v58, -v59, s[84:85]
	v_cndmask_b32_e64 v63, v60, -v61, s[84:85]
	s_nop 1
	v_mfma_f32_16x16x4_f32 v[20:23], v62, v29, v[20:23]
	v_mfma_f32_16x16x4_f32 v[24:27], v63, v29, v[24:27]
	s_cmp_eq_u32 s98, 0
	s_cselect_b64 s[4:5], -1, 0
	s_waitcnt vmcnt(0)
	s_nop 10
	v_lshl_add_u32 v19, v13, 2, 0
	v_cmp_eq_u32_e32 vcc, v19, v12
	s_nop 3
	s_and_b64 vcc, vcc, s[4:5]
	s_nop 3
	v_cndmask_b32_e32 v19, 0, v18, vcc
	v_add_f32_e32 v20, v20, v19
	v_lshl_add_u32 v19, v13, 2, 1
	v_cmp_eq_u32_e32 vcc, v19, v12
	s_nop 3
	s_and_b64 vcc, vcc, s[4:5]
	s_nop 3
	v_cndmask_b32_e32 v19, 0, v18, vcc
	v_add_f32_e32 v21, v21, v19
	v_lshl_add_u32 v19, v13, 2, 2
	v_cmp_eq_u32_e32 vcc, v19, v12
	s_nop 3
	s_and_b64 vcc, vcc, s[4:5]
	s_nop 3
	v_cndmask_b32_e32 v19, 0, v18, vcc
	v_add_f32_e32 v22, v22, v19
	v_lshl_add_u32 v19, v13, 2, 3
	v_cmp_eq_u32_e32 vcc, v19, v12
	s_nop 3
	s_and_b64 vcc, vcc, s[4:5]
	s_nop 3
	v_cndmask_b32_e32 v19, 0, v18, vcc
	v_add_f32_e32 v23, v23, v19
	s_lshl_b32 s86, s97, 6
	s_lshl_b32 s87, s82, 8
	s_mov_b32 s91, 0
	ds_write_b32 v17, v20 offset:25088
	ds_write_b32 v17, v21 offset:25152
	ds_write_b32 v17, v22 offset:25216
	ds_write_b32 v17, v23 offset:25280
	ds_write_b32 v17, v24 offset:26112
	ds_write_b32 v17, v25 offset:26176
	ds_write_b32 v17, v26 offset:26240
	ds_write_b32 v17, v27 offset:26304
	s_waitcnt lgkmcnt(0)
	s_barrier
	s_branch .Lssa_493
